# v38: + P6 tail-row-tile k-loops: waves 4-7 (rows beyond T) skip fragment reads and MFMAs
# speedup vs baseline: 1.1493x; 1.0040x over previous
.LBB0_3341:
	v_readfirstlane_b32 s64, v208
	s_cmp_lg_u32 s41, 0
	s_cbranch_scc1 .Ltrim_LBB0_3341
	s_waitcnt vmcnt(0)
.Ltrim_LBB0_3341:
	s_bitcmp1_b32 s41, 0
	s_cselect_b32 s46, 0x12000, 0
	v_add3_u32 v150, s46, v67, v69
	v_add3_u32 v151, s46, v68, v69
	s_bitcmp1_b32 s64, 8
	s_cbranch_scc1 .Lts_0_0
	ds_read_b128 v[70:73], v150
	ds_read_b128 v[74:77], v151 offset:36864
	ds_read_b128 v[78:81], v150 offset:32
	ds_read_b128 v[130:133], v151 offset:36896
	ds_read_b128 v[134:137], v151 offset:41472
	ds_read_b128 v[138:141], v151 offset:41504
	s_waitcnt lgkmcnt(4)
	v_mfma_f32_32x32x16_bf16 v[114:129], v[70:73], v[74:77], v[114:129]
.Lts_0_0:
	s_add_i32 s41, s41, 1
	s_bitcmp1_b32 s41, 0
	s_cselect_b32 s46, 0x12000, 0
	v_add_u32_e32 v152, s46, v66
	v_lshl_add_u64 v[146:147], s[24:25], 0, v[54:55]
	v_lshl_add_u64 v[148:149], s[24:25], 0, v[56:57]
	s_bitcmp1_b32 s64, 8
	s_cbranch_scc1 .Lts_0_1
	s_waitcnt lgkmcnt(1)
	v_mfma_f32_32x32x16_bf16 v[98:113], v[70:73], v[134:137], v[98:113]
	ds_read_b128 v[70:73], v150 offset:4608
	ds_read_b128 v[142:145], v150 offset:4640
.Lts_0_1:
	s_waitcnt vmcnt(4)
	ds_write_b128 v152, v[2:5]
	ds_write_b128 v152, v[6:9] offset:9216
	s_bitcmp1_b32 s64, 8
	s_cbranch_scc1 .Lts_0_2
	s_waitcnt lgkmcnt(3)
	v_mfma_f32_32x32x16_bf16 v[82:97], v[70:73], v[74:77], v[82:97]
	v_mfma_f32_32x32x16_bf16 v[34:49], v[70:73], v[134:137], v[34:49]
.Lts_0_2:
	v_lshl_add_u64 v[70:71], s[24:25], 0, v[50:51]
	v_lshl_add_u64 v[72:73], s[24:25], 0, v[52:53]
	global_load_dwordx4 v[2:5], v[70:71], off
	s_bitcmp1_b32 s64, 8
	s_cbranch_scc1 .Lts_0_3
	v_mfma_f32_32x32x16_bf16 v[114:129], v[78:81], v[130:133], v[114:129]
	v_mfma_f32_32x32x16_bf16 v[98:113], v[78:81], v[138:141], v[98:113]
	ds_read_b128 v[70:73], v150 offset:64
	ds_read_b128 v[74:77], v150 offset:4672
	ds_read_b128 v[78:81], v151 offset:36928
	ds_read_b128 v[134:137], v151 offset:41536
.Lts_0_3:
	ds_write_b128 v152, v[10:13] offset:18432
	ds_write_b128 v152, v[14:17] offset:27648
	s_bitcmp1_b32 s64, 8
	s_cbranch_scc1 .Lts_0_4
	s_waitcnt lgkmcnt(8)
	v_mfma_f32_32x32x16_bf16 v[82:97], v[142:145], v[130:133], v[82:97]
	v_mfma_f32_32x32x16_bf16 v[34:49], v[142:145], v[138:141], v[34:49]
.Lts_0_4:
	v_lshl_add_u64 v[138:139], s[24:25], 0, v[58:59]
	v_lshl_add_u64 v[140:141], s[24:25], 0, v[62:63]
	v_lshl_add_u64 v[142:143], s[24:25], 0, v[60:61]
	v_lshl_add_u64 v[144:145], s[24:25], 0, v[64:65]
	s_bitcmp1_b32 s64, 8
	s_cbranch_scc1 .Lts_0_5
	s_waitcnt lgkmcnt(3)
	v_mfma_f32_32x32x16_bf16 v[114:129], v[70:73], v[78:81], v[114:129]
	s_waitcnt lgkmcnt(2)
	v_mfma_f32_32x32x16_bf16 v[98:113], v[70:73], v[134:137], v[98:113]
	v_mfma_f32_32x32x16_bf16 v[82:97], v[74:77], v[78:81], v[82:97]
	v_mfma_f32_32x32x16_bf16 v[34:49], v[74:77], v[134:137], v[34:49]
	ds_read_b128 v[70:73], v150 offset:96
	ds_read_b128 v[74:77], v151 offset:36960
	ds_read_b128 v[78:81], v150 offset:4704
	ds_read_b128 v[130:133], v151 offset:41568
.Lts_0_5:
	s_waitcnt vmcnt(4)
	ds_write_b128 v152, v[18:21] offset:36864
	s_waitcnt vmcnt(2)
	ds_write_b128 v152, v[22:25] offset:46080
	s_waitcnt vmcnt(3)
	ds_write_b128 v152, v[26:29] offset:55296
	s_waitcnt vmcnt(1)
	ds_write_b128 v152, v[30:33] offset:64512
	global_load_dwordx4 v[18:21], v[138:139], off
	global_load_dwordx4 v[26:29], v[140:141], off
	global_load_dwordx4 v[22:25], v[142:143], off
	global_load_dwordx4 v[30:33], v[144:145], off
	s_bitcmp1_b32 s64, 8
	s_cbranch_scc1 .Lts_0_6
	s_waitcnt lgkmcnt(6)
	v_mfma_f32_32x32x16_bf16 v[114:129], v[70:73], v[74:77], v[114:129]
	s_waitcnt lgkmcnt(4)
	v_mfma_f32_32x32x16_bf16 v[98:113], v[70:73], v[130:133], v[98:113]
	v_mfma_f32_32x32x16_bf16 v[82:97], v[78:81], v[74:77], v[82:97]
	v_mfma_f32_32x32x16_bf16 v[34:49], v[78:81], v[130:133], v[34:49]
.Lts_0_6:
	s_add_u32 s24, s24, 0x80
	s_addc_u32 s25, s25, 0
	s_cmp_eq_u32 s9, s41
	s_waitcnt lgkmcnt(0)
	s_barrier
	s_cbranch_scc0 .LBB0_3341
	s_cmp_ge_i32 s9, s40
	s_cbranch_scc0 .LBB0_3344
	s_branch .LBB0_3346

.LBB0_3345:
	v_readfirstlane_b32 s64, v208
	s_bitcmp1_b32 s9, 0
	s_cselect_b32 s24, 0x12000, 0
	v_add3_u32 v53, s24, v50, v52
	v_add3_u32 v67, s24, v51, v52
	s_bitcmp1_b32 s64, 8
	s_cbranch_scc1 .Lts_1_0
	ds_read_b128 v[54:57], v53
	ds_read_b128 v[58:61], v67 offset:36864
	ds_read_b128 v[62:65], v53 offset:32
	ds_read_b128 v[68:71], v67 offset:36896
	ds_read_b128 v[72:75], v67 offset:41472
	ds_read_b128 v[76:79], v67 offset:41504
	s_waitcnt lgkmcnt(4)
	v_mfma_f32_32x32x16_bf16 v[114:129], v[54:57], v[58:61], v[114:129]
.Lts_1_0:
	s_add_i32 s9, s9, 1
	s_bitcmp1_b32 s9, 0
	s_cselect_b32 s24, 0x12000, 0
	s_bitcmp1_b32 s64, 8
	s_cbranch_scc1 .Lts_1_1
	s_waitcnt lgkmcnt(1)
	v_mfma_f32_32x32x16_bf16 v[98:113], v[54:57], v[72:75], v[98:113]
	ds_read_b128 v[54:57], v53 offset:4608
	ds_read_b128 v[130:133], v53 offset:4640
	s_waitcnt lgkmcnt(1)
	v_mfma_f32_32x32x16_bf16 v[82:97], v[54:57], v[58:61], v[82:97]
	v_mfma_f32_32x32x16_bf16 v[34:49], v[54:57], v[72:75], v[34:49]
.Lts_1_1:
	v_add_u32_e32 v72, s24, v66
	s_waitcnt vmcnt(4)
	ds_write_b128 v72, v[2:5]
	s_waitcnt vmcnt(6)
	ds_write_b128 v72, v[6:9] offset:9216
	s_bitcmp1_b32 s64, 8
	s_cbranch_scc1 .Lts_1_2
	ds_read_b128 v[54:57], v53 offset:64
	v_mfma_f32_32x32x16_bf16 v[114:129], v[62:65], v[68:71], v[114:129]
	v_mfma_f32_32x32x16_bf16 v[98:113], v[62:65], v[76:79], v[98:113]
	s_waitcnt lgkmcnt(3)
	v_mfma_f32_32x32x16_bf16 v[82:97], v[130:133], v[68:71], v[82:97]
	ds_read_b128 v[58:61], v53 offset:4672
	ds_read_b128 v[62:65], v67 offset:36928
	ds_read_b128 v[68:71], v67 offset:41536
.Lts_1_2:
	s_waitcnt vmcnt(5)
	ds_write_b128 v72, v[10:13] offset:18432
	s_waitcnt vmcnt(4)
	ds_write_b128 v72, v[14:17] offset:27648
	s_bitcmp1_b32 s64, 8
	s_cbranch_scc1 .Lts_1_3
	v_mfma_f32_32x32x16_bf16 v[34:49], v[130:133], v[76:79], v[34:49]
	s_waitcnt lgkmcnt(3)
	v_mfma_f32_32x32x16_bf16 v[114:129], v[54:57], v[62:65], v[114:129]
	s_waitcnt lgkmcnt(2)
	v_mfma_f32_32x32x16_bf16 v[98:113], v[54:57], v[68:71], v[98:113]
	v_mfma_f32_32x32x16_bf16 v[82:97], v[58:61], v[62:65], v[82:97]
	v_mfma_f32_32x32x16_bf16 v[34:49], v[58:61], v[68:71], v[34:49]
	ds_read_b128 v[54:57], v53 offset:96
	ds_read_b128 v[58:61], v67 offset:36960
	ds_read_b128 v[62:65], v53 offset:4704
	ds_read_b128 v[68:71], v67 offset:41568
.Lts_1_3:
	s_waitcnt vmcnt(3)
	ds_write_b128 v72, v[18:21] offset:36864
	s_waitcnt vmcnt(1)
	ds_write_b128 v72, v[22:25] offset:46080
	ds_write_b128 v72, v[26:29] offset:55296
	s_waitcnt vmcnt(0)
	ds_write_b128 v72, v[30:33] offset:64512
	s_bitcmp1_b32 s64, 8
	s_cbranch_scc1 .Lts_1_4
	s_waitcnt lgkmcnt(6)
	v_mfma_f32_32x32x16_bf16 v[114:129], v[54:57], v[58:61], v[114:129]
	s_waitcnt lgkmcnt(4)
	v_mfma_f32_32x32x16_bf16 v[98:113], v[54:57], v[68:71], v[98:113]
	v_mfma_f32_32x32x16_bf16 v[82:97], v[62:65], v[58:61], v[82:97]
	v_mfma_f32_32x32x16_bf16 v[34:49], v[62:65], v[68:71], v[34:49]
.Lts_1_4:
	s_cmp_lt_i32 s9, s40
	s_waitcnt lgkmcnt(0)
	s_barrier
	s_cbranch_scc1 .LBB0_3345

.LBB0_3358:
	v_readfirstlane_b32 s64, v208
	s_cmp_lg_u32 s22, 0
	s_cbranch_scc1 .Ltrim_LBB0_3358
	s_waitcnt vmcnt(0)
.Ltrim_LBB0_3358:
	s_bitcmp1_b32 s22, 0
	s_cselect_b32 s23, 0x12000, 0
	v_add3_u32 v53, s23, v50, v52
	v_add3_u32 v177, s23, v51, v52
	s_bitcmp1_b32 s64, 8
	s_cbranch_scc1 .Lts_2_0
	ds_read_b128 v[54:57], v53
	ds_read_b128 v[58:61], v177 offset:36864
	ds_read_b128 v[80:83], v53 offset:32
	ds_read_b128 v[84:87], v177 offset:36896
	ds_read_b128 v[88:91], v177 offset:41472
	ds_read_b128 v[92:95], v177 offset:41504
	s_waitcnt lgkmcnt(4)
	v_mfma_f32_32x32x16_bf16 v[128:143], v[54:57], v[58:61], v[128:143]
.Lts_2_0:
	s_add_i32 s22, s22, 1
	s_bitcmp1_b32 s22, 0
	s_cselect_b32 s23, 0x12000, 0
	v_add_u32_e32 v194, s23, v176
	v_lshl_add_u64 v[62:63], s[20:21], 0, v[38:39]
	v_lshl_add_u64 v[192:193], s[20:21], 0, v[40:41]
	s_bitcmp1_b32 s64, 8
	s_cbranch_scc1 .Lts_2_1
	s_waitcnt lgkmcnt(1)
	v_mfma_f32_32x32x16_bf16 v[112:127], v[54:57], v[88:91], v[112:127]
	ds_read_b128 v[54:57], v53 offset:4608
	ds_read_b128 v[188:191], v53 offset:4640
.Lts_2_1:
	s_waitcnt vmcnt(4)
	ds_write_b128 v194, v[2:5]
	ds_write_b128 v194, v[6:9] offset:9216
	s_bitcmp1_b32 s64, 8
	s_cbranch_scc1 .Lts_2_2
	s_waitcnt lgkmcnt(3)
	v_mfma_f32_32x32x16_bf16 v[96:111], v[54:57], v[58:61], v[96:111]
	v_mfma_f32_32x32x16_bf16 v[64:79], v[54:57], v[88:91], v[64:79]
.Lts_2_2:
	v_lshl_add_u64 v[54:55], s[20:21], 0, v[34:35]
	v_lshl_add_u64 v[56:57], s[20:21], 0, v[36:37]
	global_load_dwordx4 v[2:5], v[54:55], off
	s_bitcmp1_b32 s64, 8
	s_cbranch_scc1 .Lts_2_3
	v_mfma_f32_32x32x16_bf16 v[128:143], v[80:83], v[84:87], v[128:143]
	v_mfma_f32_32x32x16_bf16 v[112:127], v[80:83], v[92:95], v[112:127]
	ds_read_b128 v[54:57], v53 offset:64
	ds_read_b128 v[58:61], v53 offset:4672
	ds_read_b128 v[80:83], v177 offset:36928
	ds_read_b128 v[88:91], v177 offset:41536
.Lts_2_3:
	ds_write_b128 v194, v[10:13] offset:18432
	ds_write_b128 v194, v[14:17] offset:27648
	v_lshl_add_u64 v[62:63], s[20:21], 0, v[42:43]
	s_bitcmp1_b32 s64, 8
	s_cbranch_scc1 .Lts_2_4
	s_waitcnt lgkmcnt(8)
	v_mfma_f32_32x32x16_bf16 v[96:111], v[188:191], v[84:87], v[96:111]
	v_mfma_f32_32x32x16_bf16 v[64:79], v[188:191], v[92:95], v[64:79]
.Lts_2_4:
	v_lshl_add_u64 v[92:93], s[20:21], 0, v[46:47]
	v_lshl_add_u64 v[94:95], s[20:21], 0, v[44:45]
	v_lshl_add_u64 v[188:189], s[20:21], 0, v[48:49]
	s_bitcmp1_b32 s64, 8
	s_cbranch_scc1 .Lts_2_5
	s_waitcnt lgkmcnt(3)
	v_mfma_f32_32x32x16_bf16 v[128:143], v[54:57], v[80:83], v[128:143]
	s_waitcnt lgkmcnt(2)
	v_mfma_f32_32x32x16_bf16 v[112:127], v[54:57], v[88:91], v[112:127]
	v_mfma_f32_32x32x16_bf16 v[96:111], v[58:61], v[80:83], v[96:111]
	v_mfma_f32_32x32x16_bf16 v[64:79], v[58:61], v[88:91], v[64:79]
	ds_read_b128 v[54:57], v53 offset:96
	ds_read_b128 v[58:61], v177 offset:36960
	ds_read_b128 v[80:83], v53 offset:4704
	ds_read_b128 v[84:87], v177 offset:41568
.Lts_2_5:
	s_waitcnt vmcnt(4)
	ds_write_b128 v194, v[18:21] offset:36864
	s_waitcnt vmcnt(2)
	ds_write_b128 v194, v[26:29] offset:46080
	s_waitcnt vmcnt(3)
	ds_write_b128 v194, v[22:25] offset:55296
	s_waitcnt vmcnt(1)
	ds_write_b128 v194, v[30:33] offset:64512
	global_load_dwordx4 v[18:21], v[62:63], off
	global_load_dwordx4 v[22:25], v[92:93], off
	global_load_dwordx4 v[26:29], v[94:95], off
	global_load_dwordx4 v[30:33], v[188:189], off
	s_bitcmp1_b32 s64, 8
	s_cbranch_scc1 .Lts_2_6
	s_waitcnt lgkmcnt(6)
	v_mfma_f32_32x32x16_bf16 v[128:143], v[54:57], v[58:61], v[128:143]
	s_waitcnt lgkmcnt(4)
	v_mfma_f32_32x32x16_bf16 v[112:127], v[54:57], v[84:87], v[112:127]
	v_mfma_f32_32x32x16_bf16 v[96:111], v[80:83], v[58:61], v[96:111]
	v_mfma_f32_32x32x16_bf16 v[64:79], v[80:83], v[84:87], v[64:79]
.Lts_2_6:
	s_add_u32 s20, s20, 0x80
	s_addc_u32 s21, s21, 0
	s_cmp_eq_u32 s11, s22
	s_waitcnt lgkmcnt(0)
	s_barrier
	s_cbranch_scc0 .LBB0_3358
	s_mov_b32 s20, s11
	s_cmp_ge_i32 s20, s9
	s_cbranch_scc0 .LBB0_3362
	s_branch .LBB0_3364

.LBB0_3363:
	v_readfirstlane_b32 s64, v208
	s_bitcmp1_b32 s20, 0
	s_cselect_b32 s21, 0x12000, 0
	v_add3_u32 v37, s21, v34, v36
	v_add3_u32 v62, s21, v35, v36
	s_bitcmp1_b32 s64, 8
	s_cbranch_scc1 .Lts_3_0
	ds_read_b128 v[38:41], v37
	ds_read_b128 v[42:45], v62 offset:36864
	ds_read_b128 v[46:49], v37 offset:32
	ds_read_b128 v[50:53], v62 offset:36896
	ds_read_b128 v[54:57], v62 offset:41472
	ds_read_b128 v[58:61], v62 offset:41504
	s_waitcnt lgkmcnt(4)
	v_mfma_f32_32x32x16_bf16 v[128:143], v[38:41], v[42:45], v[128:143]
.Lts_3_0:
	s_add_i32 s20, s20, 1
	s_bitcmp1_b32 s20, 0
	s_cselect_b32 s21, 0x12000, 0
	s_bitcmp1_b32 s64, 8
	s_cbranch_scc1 .Lts_3_1
	s_waitcnt lgkmcnt(1)
	v_mfma_f32_32x32x16_bf16 v[112:127], v[38:41], v[54:57], v[112:127]
	ds_read_b128 v[38:41], v37 offset:4608
	ds_read_b128 v[80:83], v37 offset:4640
	s_waitcnt lgkmcnt(1)
	v_mfma_f32_32x32x16_bf16 v[96:111], v[38:41], v[42:45], v[96:111]
	v_mfma_f32_32x32x16_bf16 v[64:79], v[38:41], v[54:57], v[64:79]
.Lts_3_1:
	v_add_u32_e32 v54, s21, v176
	s_waitcnt vmcnt(4)
	ds_write_b128 v54, v[2:5]
	s_waitcnt vmcnt(6)
	ds_write_b128 v54, v[6:9] offset:9216
	s_bitcmp1_b32 s64, 8
	s_cbranch_scc1 .Lts_3_2
	ds_read_b128 v[38:41], v37 offset:64
	v_mfma_f32_32x32x16_bf16 v[128:143], v[46:49], v[50:53], v[128:143]
	v_mfma_f32_32x32x16_bf16 v[112:127], v[46:49], v[58:61], v[112:127]
	s_waitcnt lgkmcnt(3)
	v_mfma_f32_32x32x16_bf16 v[96:111], v[80:83], v[50:53], v[96:111]
	ds_read_b128 v[42:45], v37 offset:4672
	ds_read_b128 v[46:49], v62 offset:36928
	ds_read_b128 v[50:53], v62 offset:41536
.Lts_3_2:
	s_waitcnt vmcnt(5)
	ds_write_b128 v54, v[10:13] offset:18432
	s_waitcnt vmcnt(4)
	ds_write_b128 v54, v[14:17] offset:27648
	s_bitcmp1_b32 s64, 8
	s_cbranch_scc1 .Lts_3_3
	v_mfma_f32_32x32x16_bf16 v[64:79], v[80:83], v[58:61], v[64:79]
	s_waitcnt lgkmcnt(3)
	v_mfma_f32_32x32x16_bf16 v[128:143], v[38:41], v[46:49], v[128:143]
	s_waitcnt lgkmcnt(2)
	v_mfma_f32_32x32x16_bf16 v[112:127], v[38:41], v[50:53], v[112:127]
	v_mfma_f32_32x32x16_bf16 v[96:111], v[42:45], v[46:49], v[96:111]
	v_mfma_f32_32x32x16_bf16 v[64:79], v[42:45], v[50:53], v[64:79]
	ds_read_b128 v[38:41], v37 offset:96
	ds_read_b128 v[42:45], v62 offset:36960
	ds_read_b128 v[46:49], v37 offset:4704
	ds_read_b128 v[50:53], v62 offset:41568
.Lts_3_3:
	s_waitcnt vmcnt(3)
	ds_write_b128 v54, v[18:21] offset:36864
	s_waitcnt vmcnt(1)
	ds_write_b128 v54, v[26:29] offset:46080
	ds_write_b128 v54, v[22:25] offset:55296
	s_waitcnt vmcnt(0)
	ds_write_b128 v54, v[30:33] offset:64512
	s_bitcmp1_b32 s64, 8
	s_cbranch_scc1 .Lts_3_4
	s_waitcnt lgkmcnt(6)
	v_mfma_f32_32x32x16_bf16 v[128:143], v[38:41], v[42:45], v[128:143]
	s_waitcnt lgkmcnt(4)
	v_mfma_f32_32x32x16_bf16 v[112:127], v[38:41], v[50:53], v[112:127]
	v_mfma_f32_32x32x16_bf16 v[96:111], v[46:49], v[42:45], v[96:111]
	v_mfma_f32_32x32x16_bf16 v[64:79], v[46:49], v[50:53], v[64:79]
.Lts_3_4:
	s_cmp_lt_i32 s20, s9
	s_waitcnt lgkmcnt(0)
	s_barrier
	s_cbranch_scc1 .LBB0_3363

.LBB0_3384:
	v_readfirstlane_b32 s64, v208
	s_cmp_lg_u32 s35, 0
	s_cbranch_scc1 .Ltrim_LBB0_3384
	s_waitcnt vmcnt(0)
.Ltrim_LBB0_3384:
	s_bitcmp1_b32 s35, 0
	s_cselect_b32 s36, 0x12000, 0
	v_add3_u32 v69, s36, v66, v68
	v_add3_u32 v177, s36, v67, v68
	s_bitcmp1_b32 s64, 8
	s_cbranch_scc1 .Lts_4_0
	ds_read_b128 v[70:73], v69
	ds_read_b128 v[74:77], v177 offset:36864
	ds_read_b128 v[96:99], v69 offset:32
	ds_read_b128 v[100:103], v177 offset:36896
	ds_read_b128 v[104:107], v177 offset:41472
	ds_read_b128 v[108:111], v177 offset:41504
	s_waitcnt lgkmcnt(4)
	v_mfma_f32_32x32x16_bf16 v[128:143], v[70:73], v[74:77], v[128:143]
.Lts_4_0:
	s_add_i32 s35, s35, 1
	s_bitcmp1_b32 s35, 0
	s_cselect_b32 s36, 0x12000, 0
	v_add_u32_e32 v194, s36, v176
	v_lshl_add_u64 v[78:79], s[14:15], 0, v[38:39]
	v_lshl_add_u64 v[192:193], s[14:15], 0, v[40:41]
	s_bitcmp1_b32 s64, 8
	s_cbranch_scc1 .Lts_4_1
	s_waitcnt lgkmcnt(1)
	v_mfma_f32_32x32x16_bf16 v[112:127], v[70:73], v[104:107], v[112:127]
	ds_read_b128 v[70:73], v69 offset:4608
	ds_read_b128 v[188:191], v69 offset:4640
.Lts_4_1:
	s_waitcnt vmcnt(4)
	ds_write_b128 v194, v[2:5]
	ds_write_b128 v194, v[6:9] offset:9216
	s_bitcmp1_b32 s64, 8
	s_cbranch_scc1 .Lts_4_2
	s_waitcnt lgkmcnt(3)
	v_mfma_f32_32x32x16_bf16 v[80:95], v[70:73], v[74:77], v[80:95]
	v_mfma_f32_32x32x16_bf16 v[48:63], v[70:73], v[104:107], v[48:63]
.Lts_4_2:
	v_lshl_add_u64 v[70:71], s[14:15], 0, v[34:35]
	v_lshl_add_u64 v[72:73], s[14:15], 0, v[36:37]
	global_load_dwordx4 v[2:5], v[70:71], off
	s_bitcmp1_b32 s64, 8
	s_cbranch_scc1 .Lts_4_3
	v_mfma_f32_32x32x16_bf16 v[128:143], v[96:99], v[100:103], v[128:143]
	v_mfma_f32_32x32x16_bf16 v[112:127], v[96:99], v[108:111], v[112:127]
	ds_read_b128 v[70:73], v69 offset:64
	ds_read_b128 v[74:77], v69 offset:4672
	ds_read_b128 v[96:99], v177 offset:36928
	ds_read_b128 v[104:107], v177 offset:41536
.Lts_4_3:
	ds_write_b128 v194, v[10:13] offset:18432
	ds_write_b128 v194, v[14:17] offset:27648
	v_lshl_add_u64 v[78:79], s[14:15], 0, v[42:43]
	s_bitcmp1_b32 s64, 8
	s_cbranch_scc1 .Lts_4_4
	s_waitcnt lgkmcnt(8)
	v_mfma_f32_32x32x16_bf16 v[80:95], v[188:191], v[100:103], v[80:95]
	v_mfma_f32_32x32x16_bf16 v[48:63], v[188:191], v[108:111], v[48:63]
.Lts_4_4:
	v_lshl_add_u64 v[108:109], s[14:15], 0, v[46:47]
	v_lshl_add_u64 v[110:111], s[14:15], 0, v[44:45]
	v_lshl_add_u64 v[188:189], s[14:15], 0, v[64:65]
	s_bitcmp1_b32 s64, 8
	s_cbranch_scc1 .Lts_4_5
	s_waitcnt lgkmcnt(3)
	v_mfma_f32_32x32x16_bf16 v[128:143], v[70:73], v[96:99], v[128:143]
	s_waitcnt lgkmcnt(2)
	v_mfma_f32_32x32x16_bf16 v[112:127], v[70:73], v[104:107], v[112:127]
	v_mfma_f32_32x32x16_bf16 v[80:95], v[74:77], v[96:99], v[80:95]
	v_mfma_f32_32x32x16_bf16 v[48:63], v[74:77], v[104:107], v[48:63]
	ds_read_b128 v[70:73], v69 offset:96
	ds_read_b128 v[74:77], v177 offset:36960
	ds_read_b128 v[96:99], v69 offset:4704
	ds_read_b128 v[100:103], v177 offset:41568
.Lts_4_5:
	s_waitcnt vmcnt(4)
	ds_write_b128 v194, v[18:21] offset:36864
	s_waitcnt vmcnt(2)
	ds_write_b128 v194, v[26:29] offset:46080
	s_waitcnt vmcnt(3)
	ds_write_b128 v194, v[22:25] offset:55296
	s_waitcnt vmcnt(1)
	ds_write_b128 v194, v[30:33] offset:64512
	global_load_dwordx4 v[18:21], v[78:79], off
	global_load_dwordx4 v[22:25], v[108:109], off
	global_load_dwordx4 v[26:29], v[110:111], off
	global_load_dwordx4 v[30:33], v[188:189], off
	s_bitcmp1_b32 s64, 8
	s_cbranch_scc1 .Lts_4_6
	s_waitcnt lgkmcnt(6)
	v_mfma_f32_32x32x16_bf16 v[128:143], v[70:73], v[74:77], v[128:143]
	s_waitcnt lgkmcnt(4)
	v_mfma_f32_32x32x16_bf16 v[112:127], v[70:73], v[100:103], v[112:127]
	v_mfma_f32_32x32x16_bf16 v[80:95], v[96:99], v[74:77], v[80:95]
	v_mfma_f32_32x32x16_bf16 v[48:63], v[96:99], v[100:103], v[48:63]
.Lts_4_6:
	s_add_u32 s14, s14, 0x80
	s_addc_u32 s15, s15, 0
	s_cmp_eq_u32 s34, s35
	s_waitcnt lgkmcnt(0)
	s_barrier
	s_cbranch_scc0 .LBB0_3384
	s_mov_b32 s14, s34
	s_cmp_ge_i32 s14, s33
	s_cbranch_scc0 .LBB0_3387
	s_branch .LBB0_3389

.LBB0_3388:
	v_readfirstlane_b32 s64, v208
	s_bitcmp1_b32 s14, 0
	s_cselect_b32 s15, 0x12000, 0
	v_add3_u32 v37, s15, v34, v36
	v_add3_u32 v46, s15, v35, v36
	s_bitcmp1_b32 s64, 8
	s_cbranch_scc1 .Lts_5_0
	ds_read_b128 v[38:41], v37
	ds_read_b128 v[42:45], v46 offset:36864
	ds_read_b128 v[64:67], v37 offset:32
	ds_read_b128 v[68:71], v46 offset:36896
	ds_read_b128 v[72:75], v46 offset:41472
	ds_read_b128 v[76:79], v46 offset:41504
	s_waitcnt lgkmcnt(4)
	v_mfma_f32_32x32x16_bf16 v[128:143], v[38:41], v[42:45], v[128:143]
.Lts_5_0:
	s_add_i32 s14, s14, 1
	s_bitcmp1_b32 s14, 0
	s_cselect_b32 s15, 0x12000, 0
	v_add_u32_e32 v47, s15, v176
	s_bitcmp1_b32 s64, 8
	s_cbranch_scc1 .Lts_5_1
	s_waitcnt lgkmcnt(1)
	v_mfma_f32_32x32x16_bf16 v[112:127], v[38:41], v[72:75], v[112:127]
	ds_read_b128 v[38:41], v37 offset:4608
	ds_read_b128 v[96:99], v37 offset:4640
.Lts_5_1:
	s_waitcnt vmcnt(4)
	ds_write_b128 v47, v[2:5]
	s_waitcnt vmcnt(6)
	ds_write_b128 v47, v[6:9] offset:9216
	s_bitcmp1_b32 s64, 8
	s_cbranch_scc1 .Lts_5_2
	s_waitcnt lgkmcnt(3)
	v_mfma_f32_32x32x16_bf16 v[80:95], v[38:41], v[42:45], v[80:95]
	v_mfma_f32_32x32x16_bf16 v[48:63], v[38:41], v[72:75], v[48:63]
	ds_read_b128 v[38:41], v37 offset:64
	v_mfma_f32_32x32x16_bf16 v[128:143], v[64:67], v[68:71], v[128:143]
	v_mfma_f32_32x32x16_bf16 v[112:127], v[64:67], v[76:79], v[112:127]
	s_waitcnt lgkmcnt(3)
	v_mfma_f32_32x32x16_bf16 v[80:95], v[96:99], v[68:71], v[80:95]
	ds_read_b128 v[42:45], v37 offset:4672
	ds_read_b128 v[64:67], v46 offset:36928
	ds_read_b128 v[68:71], v46 offset:41536
.Lts_5_2:
	s_waitcnt vmcnt(5)
	ds_write_b128 v47, v[10:13] offset:18432
	s_waitcnt vmcnt(4)
	ds_write_b128 v47, v[14:17] offset:27648
	s_bitcmp1_b32 s64, 8
	s_cbranch_scc1 .Lts_5_3
	v_mfma_f32_32x32x16_bf16 v[48:63], v[96:99], v[76:79], v[48:63]
	s_waitcnt lgkmcnt(3)
	v_mfma_f32_32x32x16_bf16 v[128:143], v[38:41], v[64:67], v[128:143]
	s_waitcnt lgkmcnt(2)
	v_mfma_f32_32x32x16_bf16 v[112:127], v[38:41], v[68:71], v[112:127]
	v_mfma_f32_32x32x16_bf16 v[80:95], v[42:45], v[64:67], v[80:95]
	v_mfma_f32_32x32x16_bf16 v[48:63], v[42:45], v[68:71], v[48:63]
	ds_read_b128 v[38:41], v37 offset:96
	ds_read_b128 v[42:45], v46 offset:36960
	ds_read_b128 v[64:67], v37 offset:4704
	ds_read_b128 v[68:71], v46 offset:41568
.Lts_5_3:
	s_waitcnt vmcnt(3)
	ds_write_b128 v47, v[18:21] offset:36864
	s_waitcnt vmcnt(1)
	ds_write_b128 v47, v[26:29] offset:46080
	ds_write_b128 v47, v[22:25] offset:55296
	s_waitcnt vmcnt(0)
	ds_write_b128 v47, v[30:33] offset:64512
	s_bitcmp1_b32 s64, 8
	s_cbranch_scc1 .Lts_5_4
	s_waitcnt lgkmcnt(6)
	v_mfma_f32_32x32x16_bf16 v[128:143], v[38:41], v[42:45], v[128:143]
	s_waitcnt lgkmcnt(4)
	v_mfma_f32_32x32x16_bf16 v[112:127], v[38:41], v[68:71], v[112:127]
	v_mfma_f32_32x32x16_bf16 v[80:95], v[64:67], v[42:45], v[80:95]
	v_mfma_f32_32x32x16_bf16 v[48:63], v[64:67], v[68:71], v[48:63]
.Lts_5_4:
	s_cmp_lt_i32 s14, s33
	s_waitcnt lgkmcnt(0)
	s_barrier
	s_cbranch_scc1 .LBB0_3388

.LBB0_3399:
	v_readfirstlane_b32 s64, v208
	s_cmp_lg_u32 s14, 0
	s_cbranch_scc1 .Ltrim_LBB0_3399
	s_waitcnt vmcnt(0)
.Ltrim_LBB0_3399:
	s_bitcmp1_b32 s14, 0
	s_cselect_b32 s15, 0x12000, 0
	v_add3_u32 v53, s15, v50, v52
	v_add3_u32 v177, s15, v51, v52
	s_bitcmp1_b32 s64, 8
	s_cbranch_scc1 .Lts_6_0
	ds_read_b128 v[54:57], v53
	ds_read_b128 v[58:61], v177 offset:36864
	ds_read_b128 v[62:65], v53 offset:32
	ds_read_b128 v[66:69], v177 offset:36896
	ds_read_b128 v[70:73], v177 offset:41472
	ds_read_b128 v[74:77], v177 offset:41504
	s_waitcnt lgkmcnt(4)
	v_mfma_f32_32x32x16_bf16 v[128:143], v[54:57], v[58:61], v[128:143]
.Lts_6_0:
	s_add_i32 s14, s14, 1
	s_bitcmp1_b32 s14, 0
	s_cselect_b32 s15, 0x12000, 0
	v_add_u32_e32 v194, s15, v176
	v_lshl_add_u64 v[78:79], s[12:13], 0, v[38:39]
	v_lshl_add_u64 v[192:193], s[12:13], 0, v[40:41]
	s_bitcmp1_b32 s64, 8
	s_cbranch_scc1 .Lts_6_1
	s_waitcnt lgkmcnt(1)
	v_mfma_f32_32x32x16_bf16 v[112:127], v[54:57], v[70:73], v[112:127]
	ds_read_b128 v[54:57], v53 offset:4608
	ds_read_b128 v[188:191], v53 offset:4640
.Lts_6_1:
	s_waitcnt vmcnt(4)
	ds_write_b128 v194, v[2:5]
	ds_write_b128 v194, v[6:9] offset:9216
	s_bitcmp1_b32 s64, 8
	s_cbranch_scc1 .Lts_6_2
	s_waitcnt lgkmcnt(3)
	v_mfma_f32_32x32x16_bf16 v[96:111], v[54:57], v[58:61], v[96:111]
	v_mfma_f32_32x32x16_bf16 v[80:95], v[54:57], v[70:73], v[80:95]
.Lts_6_2:
	v_lshl_add_u64 v[54:55], s[12:13], 0, v[34:35]
	v_lshl_add_u64 v[56:57], s[12:13], 0, v[36:37]
	global_load_dwordx4 v[2:5], v[54:55], off
	s_bitcmp1_b32 s64, 8
	s_cbranch_scc1 .Lts_6_3
	v_mfma_f32_32x32x16_bf16 v[128:143], v[62:65], v[66:69], v[128:143]
	v_mfma_f32_32x32x16_bf16 v[112:127], v[62:65], v[74:77], v[112:127]
	ds_read_b128 v[54:57], v53 offset:64
	ds_read_b128 v[58:61], v53 offset:4672
	ds_read_b128 v[62:65], v177 offset:36928
	ds_read_b128 v[70:73], v177 offset:41536
.Lts_6_3:
	ds_write_b128 v194, v[10:13] offset:18432
	ds_write_b128 v194, v[14:17] offset:27648
	v_lshl_add_u64 v[78:79], s[12:13], 0, v[44:45]
	s_bitcmp1_b32 s64, 8
	s_cbranch_scc1 .Lts_6_4
	s_waitcnt lgkmcnt(8)
	v_mfma_f32_32x32x16_bf16 v[96:111], v[188:191], v[66:69], v[96:111]
	v_mfma_f32_32x32x16_bf16 v[80:95], v[188:191], v[74:77], v[80:95]
.Lts_6_4:
	v_lshl_add_u64 v[74:75], s[12:13], 0, v[42:43]
	v_lshl_add_u64 v[76:77], s[12:13], 0, v[46:47]
	v_lshl_add_u64 v[188:189], s[12:13], 0, v[48:49]
	s_bitcmp1_b32 s64, 8
	s_cbranch_scc1 .Lts_6_5
	s_waitcnt lgkmcnt(3)
	v_mfma_f32_32x32x16_bf16 v[128:143], v[54:57], v[62:65], v[128:143]
	s_waitcnt lgkmcnt(2)
	v_mfma_f32_32x32x16_bf16 v[112:127], v[54:57], v[70:73], v[112:127]
	v_mfma_f32_32x32x16_bf16 v[96:111], v[58:61], v[62:65], v[96:111]
	v_mfma_f32_32x32x16_bf16 v[80:95], v[58:61], v[70:73], v[80:95]
	ds_read_b128 v[54:57], v53 offset:96
	ds_read_b128 v[58:61], v177 offset:36960
	ds_read_b128 v[62:65], v53 offset:4704
	ds_read_b128 v[66:69], v177 offset:41568
.Lts_6_5:
	s_waitcnt vmcnt(4)
	ds_write_b128 v194, v[18:21] offset:36864
	s_waitcnt vmcnt(2)
	ds_write_b128 v194, v[26:29] offset:46080
	s_waitcnt vmcnt(3)
	ds_write_b128 v194, v[22:25] offset:55296
	s_waitcnt vmcnt(1)
	ds_write_b128 v194, v[30:33] offset:64512
	global_load_dwordx4 v[18:21], v[74:75], off
	global_load_dwordx4 v[22:25], v[76:77], off
	global_load_dwordx4 v[26:29], v[78:79], off
	global_load_dwordx4 v[30:33], v[188:189], off
	s_bitcmp1_b32 s64, 8
	s_cbranch_scc1 .Lts_6_6
	s_waitcnt lgkmcnt(6)
	v_mfma_f32_32x32x16_bf16 v[128:143], v[54:57], v[58:61], v[128:143]
	s_waitcnt lgkmcnt(4)
	v_mfma_f32_32x32x16_bf16 v[112:127], v[54:57], v[66:69], v[112:127]
	v_mfma_f32_32x32x16_bf16 v[96:111], v[62:65], v[58:61], v[96:111]
	v_mfma_f32_32x32x16_bf16 v[80:95], v[62:65], v[66:69], v[80:95]
.Lts_6_6:
	s_add_u32 s12, s12, 0x80
	s_addc_u32 s13, s13, 0
	s_cmp_eq_u32 s7, s14
	s_waitcnt lgkmcnt(0)
	s_barrier
	s_cbranch_scc0 .LBB0_3399
	s_mov_b32 s12, s7
	s_cmp_ge_i32 s12, s1
	s_cbranch_scc0 .LBB0_3403
	s_branch .LBB0_3405

.LBB0_3404:
	v_readfirstlane_b32 s64, v208
	s_bitcmp1_b32 s12, 0
	s_cselect_b32 s13, 0x12000, 0
	v_add3_u32 v37, s13, v34, v36
	v_add3_u32 v66, s13, v35, v36
	s_bitcmp1_b32 s64, 8
	s_cbranch_scc1 .Lts_7_0
	ds_read_b128 v[38:41], v37
	ds_read_b128 v[42:45], v66 offset:36864
	ds_read_b128 v[46:49], v37 offset:32
	ds_read_b128 v[50:53], v66 offset:36896
	ds_read_b128 v[54:57], v66 offset:41472
	ds_read_b128 v[58:61], v66 offset:41504
	s_waitcnt lgkmcnt(4)
	v_mfma_f32_32x32x16_bf16 v[128:143], v[38:41], v[42:45], v[128:143]
.Lts_7_0:
	s_add_i32 s12, s12, 1
	s_bitcmp1_b32 s12, 0
	s_cselect_b32 s13, 0x12000, 0
	s_bitcmp1_b32 s64, 8
	s_cbranch_scc1 .Lts_7_1
	s_waitcnt lgkmcnt(1)
	v_mfma_f32_32x32x16_bf16 v[112:127], v[38:41], v[54:57], v[112:127]
	ds_read_b128 v[38:41], v37 offset:4608
	ds_read_b128 v[62:65], v37 offset:4640
	s_waitcnt lgkmcnt(1)
	v_mfma_f32_32x32x16_bf16 v[96:111], v[38:41], v[42:45], v[96:111]
	v_mfma_f32_32x32x16_bf16 v[80:95], v[38:41], v[54:57], v[80:95]
.Lts_7_1:
	v_add_u32_e32 v54, s13, v176
	s_waitcnt vmcnt(4)
	ds_write_b128 v54, v[2:5]
	s_waitcnt vmcnt(6)
	ds_write_b128 v54, v[6:9] offset:9216
	s_bitcmp1_b32 s64, 8
	s_cbranch_scc1 .Lts_7_2
	ds_read_b128 v[38:41], v37 offset:64
	v_mfma_f32_32x32x16_bf16 v[128:143], v[46:49], v[50:53], v[128:143]
	v_mfma_f32_32x32x16_bf16 v[112:127], v[46:49], v[58:61], v[112:127]
	s_waitcnt lgkmcnt(3)
	v_mfma_f32_32x32x16_bf16 v[96:111], v[62:65], v[50:53], v[96:111]
	ds_read_b128 v[42:45], v37 offset:4672
	ds_read_b128 v[46:49], v66 offset:36928
	ds_read_b128 v[50:53], v66 offset:41536
.Lts_7_2:
	s_waitcnt vmcnt(5)
	ds_write_b128 v54, v[10:13] offset:18432
	s_waitcnt vmcnt(4)
	ds_write_b128 v54, v[14:17] offset:27648
	s_bitcmp1_b32 s64, 8
	s_cbranch_scc1 .Lts_7_3
	v_mfma_f32_32x32x16_bf16 v[80:95], v[62:65], v[58:61], v[80:95]
	s_waitcnt lgkmcnt(3)
	v_mfma_f32_32x32x16_bf16 v[128:143], v[38:41], v[46:49], v[128:143]
	s_waitcnt lgkmcnt(2)
	v_mfma_f32_32x32x16_bf16 v[112:127], v[38:41], v[50:53], v[112:127]
	v_mfma_f32_32x32x16_bf16 v[96:111], v[42:45], v[46:49], v[96:111]
	v_mfma_f32_32x32x16_bf16 v[80:95], v[42:45], v[50:53], v[80:95]
	ds_read_b128 v[38:41], v37 offset:96
	ds_read_b128 v[42:45], v66 offset:36960
	ds_read_b128 v[46:49], v37 offset:4704
	ds_read_b128 v[50:53], v66 offset:41568
.Lts_7_3:
	s_waitcnt vmcnt(3)
	ds_write_b128 v54, v[18:21] offset:36864
	s_waitcnt vmcnt(1)
	ds_write_b128 v54, v[26:29] offset:46080
	ds_write_b128 v54, v[22:25] offset:55296
	s_waitcnt vmcnt(0)
	ds_write_b128 v54, v[30:33] offset:64512
	s_bitcmp1_b32 s64, 8
	s_cbranch_scc1 .Lts_7_4
	s_waitcnt lgkmcnt(6)
	v_mfma_f32_32x32x16_bf16 v[128:143], v[38:41], v[42:45], v[128:143]
	s_waitcnt lgkmcnt(4)
	v_mfma_f32_32x32x16_bf16 v[112:127], v[38:41], v[50:53], v[112:127]
	v_mfma_f32_32x32x16_bf16 v[96:111], v[46:49], v[42:45], v[96:111]
	v_mfma_f32_32x32x16_bf16 v[80:95], v[46:49], v[50:53], v[80:95]
.Lts_7_4:
	s_cmp_lt_i32 s12, s1
	s_waitcnt lgkmcnt(0)
	s_barrier
	s_cbranch_scc1 .LBB0_3404
